# E35: P0 row-norm loop requests row k+1 (second landing register set, duplicated body) before reducing row k; on E34
# speedup vs baseline: 1.0120x; 1.0035x over previous
.LBB0_87:
	s_cmpk_gt_i32 s24, 0x447f
	s_cbranch_scc1 .LBB0_98
	v_and_b32_e32 v6, 64, v217
	v_add_u32_e32 v6, 64, v6
	v_xor_b32_e32 v7, 1, v217
	v_cmp_lt_i32_e32 vcc, v7, v6
	v_mov_b32_e32 v3, 0
	s_mov_b64 s[0:1], 0x3300000
	v_cndmask_b32_e32 v7, v217, v7, vcc
	v_lshlrev_b32_e32 v16, 2, v7
	v_xor_b32_e32 v7, 2, v217
	v_cmp_lt_i32_e32 vcc, v7, v6
	s_ashr_i32 s25, s24, 31
	s_lshl_b32 s28, s88, 4
	v_cndmask_b32_e32 v7, v217, v7, vcc
	v_lshlrev_b32_e32 v17, 2, v7
	v_xor_b32_e32 v7, 4, v217
	v_cmp_lt_i32_e32 vcc, v7, v6
	s_waitcnt lgkmcnt(0)
	s_add_i32 s16, s24, 0xffffbf80
	v_lshlrev_b32_e32 v12, 3, v213
	v_cndmask_b32_e32 v7, v217, v7, vcc
	v_lshlrev_b32_e32 v18, 2, v7
	v_xor_b32_e32 v7, 8, v217
	v_cmp_lt_i32_e32 vcc, v7, v6
	v_mov_b32_e32 v13, v3
	v_readlane_b32 s64, v244, 7
	v_cndmask_b32_e32 v7, v217, v7, vcc
	v_lshlrev_b32_e32 v19, 2, v7
	v_xor_b32_e32 v7, 16, v217
	v_cmp_lt_i32_e32 vcc, v7, v6
	v_readlane_b32 s65, v244, 8
	v_lshlrev_b32_e32 v2, 4, v213
	v_cndmask_b32_e32 v7, v217, v7, vcc
	v_lshlrev_b32_e32 v20, 2, v7
	v_xor_b32_e32 v7, 32, v217
	v_cmp_lt_i32_e32 vcc, v7, v6
	v_readlane_b32 s66, v244, 9
	v_readlane_b32 s67, v244, 10
	v_cndmask_b32_e32 v6, v217, v7, vcc
	v_lshlrev_b32_e32 v21, 2, v6
	v_and_b32_e32 v6, 4, v162
	v_lshlrev_b32_e32 v6, 1, v6
	v_mov_b32_e32 v7, v3
	v_lshl_add_u64 v[10:11], s[82:83], 0, v[6:7]
	v_lshl_add_u64 v[6:7], v[10:11], 0, s[0:1]
	s_mov_b64 s[0:1], 0x6100000
	v_lshl_add_u64 v[10:11], v[10:11], 0, s[0:1]
	s_lshl_b32 s0, s2, 4
	s_lshl_b32 s1, s3, 1
	s_add_i32 s3, s0, s1
	s_lshl_b64 s[0:1], s[24:25], 11
	s_add_u32 s0, s82, s0
	s_addc_u32 s1, s83, s1
	v_lshl_add_u64 v[12:13], s[0:1], 0, v[12:13]
	s_mov_b64 s[0:1], 0x4100000
	s_ashr_i32 s7, s6, 31
	v_lshl_add_u64 v[12:13], v[12:13], 0, s[0:1]
	s_lshl_b64 s[18:19], s[6:7], 11
	s_lshl_b64 s[0:1], s[24:25], 12
	s_add_u32 s0, s64, s0
	s_addc_u32 s1, s65, s1
	v_lshl_add_u64 v[4:5], s[48:49], 0, v[2:3]
	v_and_b32_e32 v22, 32, v2
	v_lshrrev_b32_e32 v23, 2, v213
	v_lshl_add_u64 v[8:9], s[66:67], 0, v[2:3]
	v_lshl_add_u64 v[14:15], s[0:1], 0, v[2:3]
	s_lshl_b64 s[24:25], s[6:7], 12
	s_mov_b32 s27, 0
	v_mov_b32_e32 v24, 0x358637bd
	s_mov_b32 s7, 0xf800000
	v_mov_b32_e32 v25, 0x260
	v_readlane_b32 s68, v244, 11
	v_readlane_b32 s69, v244, 12
	v_readlane_b32 s70, v244, 13
	v_readlane_b32 s71, v244, 14
	v_readlane_b32 s72, v244, 15
	v_readlane_b32 s73, v244, 16
	v_readlane_b32 s74, v244, 17
	v_readlane_b32 s75, v244, 18
	v_readlane_b32 s76, v244, 19
	v_readlane_b32 s77, v244, 20
	v_readlane_b32 s78, v244, 21
	v_readlane_b32 s79, v244, 22
	s_mov_b32 s98, 0
	s_add_i32 s99, s16, 0x4080
	s_cmpk_gt_i32 s99, 0x3fff
	s_cbranch_scc1 .LBB0_90
	global_load_dwordx4 v[26:29], v[14:15], off nt
	global_load_dwordx4 v[30:33], v[14:15], off offset:1024 nt
	global_load_dwordx4 v[34:37], v[14:15], off offset:3072 nt
	global_load_dwordx4 v[38:41], v[14:15], off offset:2048 nt
	s_branch .LBB0_90

.LBB0_96:
	s_andn2_b64 vcc, exec, s[0:1]
	s_cbranch_vccnz .LBB0_89
	s_cmp_lg_u32 s98, 0
	s_cbranch_scc1 .Lp0_setB
	s_add_i32 s99, s17, s6
	s_cmpk_gt_i32 s99, 0x3fff
	s_cbranch_scc1 .Lp0_lastA
	v_lshl_add_u64 v[58:59], v[14:15], 0, s[24:25]
	global_load_dwordx4 v[168:171], v[58:59], off nt
	global_load_dwordx4 v[172:175], v[58:59], off offset:1024 nt
	global_load_dwordx4 v[176:179], v[58:59], off offset:3072 nt
	global_load_dwordx4 v[180:183], v[58:59], off offset:2048 nt
	s_waitcnt vmcnt(4)
	s_branch .Lp0_goA

.Lp0_goA:
	v_pk_mul_f32 v[42:43], v[28:29], v[28:29]
	v_pk_mul_f32 v[44:45], v[26:27], v[26:27]
	v_pk_mul_f32 v[46:47], v[32:33], v[32:33]
	v_pk_mul_f32 v[48:49], v[30:31], v[30:31]
	v_pk_mov_b32 v[52:53], v[44:45], v[42:43] op_sel:[1,0]
	v_mov_b32_e32 v45, v43
	v_pk_mov_b32 v[42:43], v[48:49], v[46:47] op_sel:[1,0]
	v_mov_b32_e32 v49, v47
	v_mul_f32_e32 v2, v39, v39
	v_mul_f32_e32 v50, v41, v41
	v_pk_add_f32 v[44:45], v[52:53], v[44:45]
	v_pk_add_f32 v[42:43], v[42:43], v[48:49]
	v_mul_f32_e32 v54, v34, v34
	v_mul_f32_e32 v55, v35, v35
	v_mul_f32_e32 v56, v36, v36
	v_mul_f32_e32 v57, v37, v37
	v_pk_fma_f32 v[46:47], v[38:39], v[38:39], v[2:3] op_sel_hi:[1,1,0]
	v_pk_fma_f32 v[50:51], v[40:41], v[40:41], v[50:51] op_sel_hi:[1,1,0]
	v_pk_add_f32 v[44:45], v[44:45], v[44:45] op_sel:[0,1] op_sel_hi:[1,0]
	v_pk_add_f32 v[42:43], v[42:43], v[42:43] op_sel:[0,1] op_sel_hi:[1,0]
	v_mov_b32_e32 v47, v56
	v_mov_b32_e32 v51, v57
	v_mov_b32_e32 v45, v54
	v_mov_b32_e32 v43, v55
	v_pk_add_f32 v[46:47], v[46:47], v[50:51]
	v_pk_add_f32 v[42:43], v[44:45], v[42:43]
	s_nop 0
	v_pk_add_f32 v[42:43], v[42:43], v[46:47]
	s_nop 0
	v_add_f32_e32 v2, v42, v43
	ds_bpermute_b32 v42, v16, v2
	s_waitcnt lgkmcnt(0)
	v_add_f32_e32 v2, v2, v42
	ds_bpermute_b32 v42, v17, v2
	s_waitcnt lgkmcnt(0)
	v_add_f32_e32 v2, v2, v42
	ds_bpermute_b32 v42, v18, v2
	s_waitcnt lgkmcnt(0)
	v_add_f32_e32 v2, v2, v42
	ds_bpermute_b32 v42, v19, v2
	s_waitcnt lgkmcnt(0)
	v_add_f32_e32 v2, v2, v42
	ds_bpermute_b32 v42, v20, v2
	s_waitcnt lgkmcnt(0)
	v_add_f32_e32 v2, v2, v42
	ds_bpermute_b32 v42, v21, v2
	s_waitcnt lgkmcnt(0)
	v_add_f32_e32 v2, v2, v42
	v_fmamk_f32 v2, v2, 0x3a800000, v24
	v_mul_f32_e32 v42, 0x4f800000, v2
	v_cmp_gt_f32_e32 vcc, s7, v2
	s_nop 1
	v_cndmask_b32_e32 v2, v2, v42, vcc
	v_sqrt_f32_e32 v42, v2
	s_nop 0
	v_add_u32_e32 v43, -1, v42
	v_add_u32_e32 v44, 1, v42
	v_fma_f32 v45, -v43, v42, v2
	v_fma_f32 v46, -v44, v42, v2
	v_cmp_ge_f32_e64 s[0:1], 0, v45
	s_nop 1
	v_cndmask_b32_e64 v42, v42, v43, s[0:1]
	v_cmp_lt_f32_e64 s[0:1], 0, v46
	s_nop 1
	v_cndmask_b32_e64 v42, v42, v44, s[0:1]
	v_mul_f32_e32 v43, 0x37800000, v42
	v_cndmask_b32_e32 v42, v42, v43, vcc
	v_cmp_class_f32_e32 vcc, v2, v25
	s_nop 1
	v_cndmask_b32_e32 v2, v42, v2, vcc
	v_div_scale_f32 v42, s[0:1], v2, v2, 1.0
	v_rcp_f32_e32 v43, v42
	v_div_scale_f32 v44, vcc, 1.0, v2, 1.0
	v_fma_f32 v45, -v42, v43, 1.0
	v_fmac_f32_e32 v43, v45, v43
	v_mul_f32_e32 v45, v44, v43
	v_fma_f32 v46, -v42, v45, v44
	v_fmac_f32_e32 v45, v46, v43
	v_fma_f32 v42, -v42, v45, v44
	v_div_fmas_f32 v42, v42, v43, v45
	v_div_fixup_f32 v2, v42, v2, 1.0
	v_pk_mul_f32 v[26:27], v[26:27], v[2:3] op_sel_hi:[1,0]
	v_pk_mul_f32 v[28:29], v[28:29], v[2:3] op_sel_hi:[1,0]
	v_pk_mul_f32 v[30:31], v[30:31], v[2:3] op_sel_hi:[1,0]
	v_pk_mul_f32 v[32:33], v[32:33], v[2:3] op_sel_hi:[1,0]
	v_pk_mul_f32 v[38:39], v[38:39], v[2:3] op_sel_hi:[1,0]
	v_pk_mul_f32 v[40:41], v[40:41], v[2:3] op_sel_hi:[1,0]
	v_pk_mul_f32 v[34:35], v[34:35], v[2:3] op_sel_hi:[1,0]
	v_pk_mul_f32 v[36:37], v[36:37], v[2:3] op_sel_hi:[1,0]
	v_cvt_pk_bf16_f32 v26, v26, v27
	v_cvt_pk_bf16_f32 v27, v28, v29
	v_cvt_pk_bf16_f32 v28, v30, v31
	v_cvt_pk_bf16_f32 v29, v32, v33
	v_cvt_pk_bf16_f32 v30, v38, v39
	v_cvt_pk_bf16_f32 v31, v40, v41
	v_cvt_pk_bf16_f32 v32, v34, v35
	v_cvt_pk_bf16_f32 v33, v36, v37
	global_store_dwordx2 v[12:13], v[26:27], off
	global_store_dwordx2 v[12:13], v[28:29], off offset:512
	global_store_dwordx2 v[12:13], v[30:31], off offset:1024
	global_store_dwordx2 v[12:13], v[32:33], off offset:1536
	s_mov_b32 s98, 1
	s_branch .LBB0_89
.Lp0_setB:
	s_add_i32 s99, s17, s6
	s_cmpk_gt_i32 s99, 0x3fff
	s_cbranch_scc1 .Lp0_lastB
	v_lshl_add_u64 v[58:59], v[14:15], 0, s[24:25]
	global_load_dwordx4 v[26:29], v[58:59], off nt
	global_load_dwordx4 v[30:33], v[58:59], off offset:1024 nt
	global_load_dwordx4 v[34:37], v[58:59], off offset:3072 nt
	global_load_dwordx4 v[38:41], v[58:59], off offset:2048 nt
	s_waitcnt vmcnt(4)
	s_branch .Lp0_goB

.Lp0_goB:
	v_pk_mul_f32 v[42:43], v[170:171], v[170:171]
	v_pk_mul_f32 v[44:45], v[168:169], v[168:169]
	v_pk_mul_f32 v[46:47], v[174:175], v[174:175]
	v_pk_mul_f32 v[48:49], v[172:173], v[172:173]
	v_pk_mov_b32 v[52:53], v[44:45], v[42:43] op_sel:[1,0]
	v_mov_b32_e32 v45, v43
	v_pk_mov_b32 v[42:43], v[48:49], v[46:47] op_sel:[1,0]
	v_mov_b32_e32 v49, v47
	v_mul_f32_e32 v2, v181, v181
	v_mul_f32_e32 v50, v183, v183
	v_pk_add_f32 v[44:45], v[52:53], v[44:45]
	v_pk_add_f32 v[42:43], v[42:43], v[48:49]
	v_mul_f32_e32 v54, v176, v176
	v_mul_f32_e32 v55, v177, v177
	v_mul_f32_e32 v56, v178, v178
	v_mul_f32_e32 v57, v179, v179
	v_pk_fma_f32 v[46:47], v[180:181], v[180:181], v[2:3] op_sel_hi:[1,1,0]
	v_pk_fma_f32 v[50:51], v[182:183], v[182:183], v[50:51] op_sel_hi:[1,1,0]
	v_pk_add_f32 v[44:45], v[44:45], v[44:45] op_sel:[0,1] op_sel_hi:[1,0]
	v_pk_add_f32 v[42:43], v[42:43], v[42:43] op_sel:[0,1] op_sel_hi:[1,0]
	v_mov_b32_e32 v47, v56
	v_mov_b32_e32 v51, v57
	v_mov_b32_e32 v45, v54
	v_mov_b32_e32 v43, v55
	v_pk_add_f32 v[46:47], v[46:47], v[50:51]
	v_pk_add_f32 v[42:43], v[44:45], v[42:43]
	s_nop 0
	v_pk_add_f32 v[42:43], v[42:43], v[46:47]
	s_nop 0
	v_add_f32_e32 v2, v42, v43
	ds_bpermute_b32 v42, v16, v2
	s_waitcnt lgkmcnt(0)
	v_add_f32_e32 v2, v2, v42
	ds_bpermute_b32 v42, v17, v2
	s_waitcnt lgkmcnt(0)
	v_add_f32_e32 v2, v2, v42
	ds_bpermute_b32 v42, v18, v2
	s_waitcnt lgkmcnt(0)
	v_add_f32_e32 v2, v2, v42
	ds_bpermute_b32 v42, v19, v2
	s_waitcnt lgkmcnt(0)
	v_add_f32_e32 v2, v2, v42
	ds_bpermute_b32 v42, v20, v2
	s_waitcnt lgkmcnt(0)
	v_add_f32_e32 v2, v2, v42
	ds_bpermute_b32 v42, v21, v2
	s_waitcnt lgkmcnt(0)
	v_add_f32_e32 v2, v2, v42
	v_fmamk_f32 v2, v2, 0x3a800000, v24
	v_mul_f32_e32 v42, 0x4f800000, v2
	v_cmp_gt_f32_e32 vcc, s7, v2
	s_nop 1
	v_cndmask_b32_e32 v2, v2, v42, vcc
	v_sqrt_f32_e32 v42, v2
	s_nop 0
	v_add_u32_e32 v43, -1, v42
	v_add_u32_e32 v44, 1, v42
	v_fma_f32 v45, -v43, v42, v2
	v_fma_f32 v46, -v44, v42, v2
	v_cmp_ge_f32_e64 s[0:1], 0, v45
	s_nop 1
	v_cndmask_b32_e64 v42, v42, v43, s[0:1]
	v_cmp_lt_f32_e64 s[0:1], 0, v46
	s_nop 1
	v_cndmask_b32_e64 v42, v42, v44, s[0:1]
	v_mul_f32_e32 v43, 0x37800000, v42
	v_cndmask_b32_e32 v42, v42, v43, vcc
	v_cmp_class_f32_e32 vcc, v2, v25
	s_nop 1
	v_cndmask_b32_e32 v2, v42, v2, vcc
	v_div_scale_f32 v42, s[0:1], v2, v2, 1.0
	v_rcp_f32_e32 v43, v42
	v_div_scale_f32 v44, vcc, 1.0, v2, 1.0
	v_fma_f32 v45, -v42, v43, 1.0
	v_fmac_f32_e32 v43, v45, v43
	v_mul_f32_e32 v45, v44, v43
	v_fma_f32 v46, -v42, v45, v44
	v_fmac_f32_e32 v45, v46, v43
	v_fma_f32 v42, -v42, v45, v44
	v_div_fmas_f32 v42, v42, v43, v45
	v_div_fixup_f32 v2, v42, v2, 1.0
	v_pk_mul_f32 v[168:169], v[168:169], v[2:3] op_sel_hi:[1,0]
	v_pk_mul_f32 v[170:171], v[170:171], v[2:3] op_sel_hi:[1,0]
	v_pk_mul_f32 v[172:173], v[172:173], v[2:3] op_sel_hi:[1,0]
	v_pk_mul_f32 v[174:175], v[174:175], v[2:3] op_sel_hi:[1,0]
	v_pk_mul_f32 v[180:181], v[180:181], v[2:3] op_sel_hi:[1,0]
	v_pk_mul_f32 v[182:183], v[182:183], v[2:3] op_sel_hi:[1,0]
	v_pk_mul_f32 v[176:177], v[176:177], v[2:3] op_sel_hi:[1,0]
	v_pk_mul_f32 v[178:179], v[178:179], v[2:3] op_sel_hi:[1,0]
	v_cvt_pk_bf16_f32 v168, v168, v169
	v_cvt_pk_bf16_f32 v169, v170, v171
	v_cvt_pk_bf16_f32 v170, v172, v173
	v_cvt_pk_bf16_f32 v171, v174, v175
	v_cvt_pk_bf16_f32 v172, v180, v181
	v_cvt_pk_bf16_f32 v173, v182, v183
	v_cvt_pk_bf16_f32 v174, v176, v177
	v_cvt_pk_bf16_f32 v175, v178, v179
	global_store_dwordx2 v[12:13], v[168:169], off
	global_store_dwordx2 v[12:13], v[170:171], off offset:512
	global_store_dwordx2 v[12:13], v[172:173], off offset:1024
	global_store_dwordx2 v[12:13], v[174:175], off offset:1536
	s_mov_b32 s98, 0
	s_branch .LBB0_89
